# down/in_proj epilogues (P3,P5,P13): 8 row-scale loads up front, per-group vmcnt(0) removed; on top of v1
# baseline (speedup 1.0000x reference)
.LBB0_365:
	v_lshl_or_b32 v160, s92, 8, v167
	v_ashrrev_i32_e32 v161, 31, v160
	v_lshl_add_u64 v[110:111], v[160:161], 2, s[40:41]
	global_load_dwordx4 v[114:117], v[110:111], off offset:16
	global_load_dwordx4 v[122:125], v[110:111], off
	global_load_dwordx4 v[106:109], v[110:111], off offset:528
	s_nop 0
	global_load_dwordx4 v[110:113], v[110:111], off offset:512
	v_lshl_add_u32 v162, s91, 8, v1
	v_cndmask_b32_e64 v166, 0, 1, s[48:49]
	v_ashrrev_i32_e32 v163, 31, v162
	v_mov_b32_e32 v164, 0x39010204
	v_cmp_ne_u32_e64 s[6:7], 1, v166
	s_andn2_b64 vcc, exec, s[48:49]
	v_mov_b32_e32 v166, 0x39010204
	s_cbranch_vccnz .LBB0_367
	v_lshl_add_u64 v[172:173], v[162:163], 2, s[70:71]
	global_load_dword v166, v[172:173], off
	global_load_dword v200, v[172:173], off offset:64
	global_load_dword v201, v[172:173], off offset:128
	global_load_dword v202, v[172:173], off offset:192
	global_load_dword v203, v[172:173], off offset:512
	global_load_dword v204, v[172:173], off offset:576
	global_load_dword v205, v[172:173], off offset:640
	global_load_dword v206, v[172:173], off offset:704
	s_waitcnt vmcnt(0)
	v_mul_f32_e32 v166, 0x39010204, v166
.LBB0_367:
	v_cvt_f32_i32_e32 v143, v143
	v_cvt_f32_i32_e32 v145, v145
	v_cvt_f32_i32_e32 v144, v144
	v_cvt_f32_i32_e32 v142, v142
	v_cvt_f32_i32_e32 v141, v141
	v_cvt_f32_i32_e32 v139, v139
	v_cvt_f32_i32_e32 v138, v138
	v_cvt_f32_i32_e32 v140, v140
	v_cvt_f32_i32_e32 v135, v135
	v_cvt_f32_i32_e32 v134, v134
	v_cvt_f32_i32_e32 v133, v133
	v_cvt_f32_i32_e32 v131, v131
	v_cvt_f32_i32_e32 v130, v130
	v_cvt_f32_i32_e32 v132, v132
	v_cvt_f32_i32_e32 v137, v137
	v_cvt_f32_i32_e32 v136, v136
	v_lshlrev_b64 v[172:173], 13, v[162:163]
	v_lshl_add_u64 v[172:173], s[36:37], 0, v[172:173]
	s_waitcnt vmcnt(0)
	v_pk_mul_f32 v[144:145], v[124:125], v[144:145]
	v_pk_mul_f32 v[142:143], v[122:123], v[142:143]
	v_pk_mul_f32 v[138:139], v[114:115], v[138:139]
	v_pk_mul_f32 v[140:141], v[116:117], v[140:141]
	v_lshl_add_u64 v[172:173], v[160:161], 1, v[172:173]
	v_pk_mul_f32 v[144:145], v[144:145], v[166:167] op_sel_hi:[1,0]
	v_pk_mul_f32 v[142:143], v[142:143], v[166:167] op_sel_hi:[1,0]
	v_pk_mul_f32 v[174:175], v[140:141], v[166:167] op_sel_hi:[1,0]
	v_pk_mul_f32 v[140:141], v[138:139], v[166:167] op_sel_hi:[1,0]
	v_cvt_pk_bf16_f32 v138, v142, v143
	v_cvt_pk_bf16_f32 v139, v144, v145
	v_pk_mul_f32 v[134:135], v[110:111], v[134:135]
	v_pk_mul_f32 v[130:131], v[106:107], v[130:131]
	v_pk_mul_f32 v[132:133], v[108:109], v[132:133]
	v_cvt_pk_bf16_f32 v140, v140, v141
	v_cvt_pk_bf16_f32 v141, v174, v175
	global_store_dwordx4 v[172:173], v[138:141], off
	v_pk_mul_f32 v[136:137], v[112:113], v[136:137]
	v_pk_mul_f32 v[134:135], v[134:135], v[166:167] op_sel_hi:[1,0]
	v_pk_mul_f32 v[138:139], v[132:133], v[166:167] op_sel_hi:[1,0]
	v_pk_mul_f32 v[132:133], v[130:131], v[166:167] op_sel_hi:[1,0]
	v_cvt_pk_bf16_f32 v130, v134, v135
	v_pk_mul_f32 v[136:137], v[136:137], v[166:167] op_sel_hi:[1,0]
	s_and_b64 vcc, exec, s[6:7]
	v_cvt_pk_bf16_f32 v131, v136, v137
	v_cvt_pk_bf16_f32 v132, v132, v133
	v_cvt_pk_bf16_f32 v133, v138, v139
	global_store_dwordx4 v[172:173], v[130:133], off offset:256
	s_nop 1
	v_or_b32_e32 v130, 16, v162
	v_ashrrev_i32_e32 v131, 31, v130
	s_cbranch_vccnz .LBB0_369
	v_mul_f32_e32 v164, 0x39010204, v200
.LBB0_369:
	v_cvt_f32_i32_e32 v127, v127
	v_cvt_f32_i32_e32 v129, v129
	v_cvt_f32_i32_e32 v128, v128
	v_cvt_f32_i32_e32 v126, v126
	v_cvt_f32_i32_e32 v119, v119
	v_cvt_f32_i32_e32 v121, v121
	v_cvt_f32_i32_e32 v120, v120
	v_cvt_f32_i32_e32 v118, v118
	v_cvt_f32_i32_e32 v103, v103
	v_cvt_f32_i32_e32 v102, v102
	v_cvt_f32_i32_e32 v99, v99
	v_cvt_f32_i32_e32 v101, v101
	v_cvt_f32_i32_e32 v100, v100
	v_cvt_f32_i32_e32 v98, v98
	v_cvt_f32_i32_e32 v105, v105
	v_cvt_f32_i32_e32 v104, v104
	v_lshlrev_b64 v[130:131], 13, v[130:131]
	v_lshl_add_u64 v[130:131], s[36:37], 0, v[130:131]
	v_pk_mul_f32 v[128:129], v[124:125], v[128:129]
	v_pk_mul_f32 v[126:127], v[122:123], v[126:127]
	v_pk_mul_f32 v[120:121], v[116:117], v[120:121]
	v_pk_mul_f32 v[118:119], v[114:115], v[118:119]
	v_lshl_add_u64 v[130:131], v[160:161], 1, v[130:131]
	v_pk_mul_f32 v[128:129], v[128:129], v[164:165] op_sel_hi:[1,0]
	v_pk_mul_f32 v[126:127], v[126:127], v[164:165] op_sel_hi:[1,0]
	v_pk_mul_f32 v[132:133], v[120:121], v[164:165] op_sel_hi:[1,0]
	v_pk_mul_f32 v[120:121], v[118:119], v[164:165] op_sel_hi:[1,0]
	v_cvt_pk_bf16_f32 v118, v126, v127
	v_cvt_pk_bf16_f32 v119, v128, v129
	v_pk_mul_f32 v[102:103], v[110:111], v[102:103]
	v_pk_mul_f32 v[100:101], v[108:109], v[100:101]
	v_pk_mul_f32 v[98:99], v[106:107], v[98:99]
	v_cvt_pk_bf16_f32 v120, v120, v121
	v_cvt_pk_bf16_f32 v121, v132, v133
	global_store_dwordx4 v[130:131], v[118:121], off
	v_pk_mul_f32 v[104:105], v[112:113], v[104:105]
	v_pk_mul_f32 v[102:103], v[102:103], v[164:165] op_sel_hi:[1,0]
	v_pk_mul_f32 v[118:119], v[100:101], v[164:165] op_sel_hi:[1,0]
	v_pk_mul_f32 v[100:101], v[98:99], v[164:165] op_sel_hi:[1,0]
	v_pk_mul_f32 v[104:105], v[104:105], v[164:165] op_sel_hi:[1,0]
	v_cvt_pk_bf16_f32 v98, v102, v103
	v_or_b32_e32 v102, 32, v162
	v_cvt_pk_bf16_f32 v99, v104, v105
	v_cvt_pk_bf16_f32 v100, v100, v101
	v_cvt_pk_bf16_f32 v101, v118, v119
	global_store_dwordx4 v[130:131], v[98:101], off offset:256
	v_ashrrev_i32_e32 v103, 31, v102
	s_and_b64 vcc, exec, s[6:7]
	v_mov_b32_e32 v98, 0x39010204
	v_mov_b32_e32 v100, 0x39010204
	s_cbranch_vccnz .LBB0_371
	v_mul_f32_e32 v100, 0x39010204, v201
.LBB0_371:
	v_cvt_f32_i32_e32 v95, v95
	v_cvt_f32_i32_e32 v97, v97
	v_cvt_f32_i32_e32 v96, v96
	v_cvt_f32_i32_e32 v94, v94
	v_cvt_f32_i32_e32 v91, v91
	v_cvt_f32_i32_e32 v93, v93
	v_cvt_f32_i32_e32 v92, v92
	v_cvt_f32_i32_e32 v90, v90
	v_cvt_f32_i32_e32 v87, v87
	v_cvt_f32_i32_e32 v86, v86
	v_cvt_f32_i32_e32 v83, v83
	v_cvt_f32_i32_e32 v85, v85
	v_cvt_f32_i32_e32 v84, v84
	v_cvt_f32_i32_e32 v82, v82
	v_cvt_f32_i32_e32 v89, v89
	v_cvt_f32_i32_e32 v88, v88
	v_lshlrev_b64 v[102:103], 13, v[102:103]
	v_lshl_add_u64 v[102:103], s[36:37], 0, v[102:103]
	v_pk_mul_f32 v[96:97], v[124:125], v[96:97]
	v_pk_mul_f32 v[94:95], v[122:123], v[94:95]
	v_pk_mul_f32 v[92:93], v[116:117], v[92:93]
	v_pk_mul_f32 v[90:91], v[114:115], v[90:91]
	v_lshl_add_u64 v[102:103], v[160:161], 1, v[102:103]
	v_pk_mul_f32 v[96:97], v[96:97], v[100:101] op_sel_hi:[1,0]
	v_pk_mul_f32 v[94:95], v[94:95], v[100:101] op_sel_hi:[1,0]
	v_pk_mul_f32 v[104:105], v[92:93], v[100:101] op_sel_hi:[1,0]
	v_pk_mul_f32 v[92:93], v[90:91], v[100:101] op_sel_hi:[1,0]
	v_cvt_pk_bf16_f32 v90, v94, v95
	v_cvt_pk_bf16_f32 v91, v96, v97
	v_pk_mul_f32 v[86:87], v[110:111], v[86:87]
	v_pk_mul_f32 v[84:85], v[108:109], v[84:85]
	v_pk_mul_f32 v[82:83], v[106:107], v[82:83]
	v_cvt_pk_bf16_f32 v92, v92, v93
	v_cvt_pk_bf16_f32 v93, v104, v105
	global_store_dwordx4 v[102:103], v[90:93], off
	v_pk_mul_f32 v[88:89], v[112:113], v[88:89]
	v_pk_mul_f32 v[86:87], v[86:87], v[100:101] op_sel_hi:[1,0]
	v_pk_mul_f32 v[90:91], v[84:85], v[100:101] op_sel_hi:[1,0]
	v_pk_mul_f32 v[84:85], v[82:83], v[100:101] op_sel_hi:[1,0]
	v_cvt_pk_bf16_f32 v82, v86, v87
	v_pk_mul_f32 v[88:89], v[88:89], v[100:101] op_sel_hi:[1,0]
	s_and_b64 vcc, exec, s[6:7]
	v_cvt_pk_bf16_f32 v83, v88, v89
	v_cvt_pk_bf16_f32 v84, v84, v85
	v_cvt_pk_bf16_f32 v85, v90, v91
	global_store_dwordx4 v[102:103], v[82:85], off offset:256
	s_nop 1
	v_or_b32_e32 v82, 48, v162
	v_ashrrev_i32_e32 v83, 31, v82
	s_cbranch_vccnz .LBB0_373
	v_mul_f32_e32 v98, 0x39010204, v202
.LBB0_373:
	v_cvt_f32_i32_e32 v79, v79
	v_cvt_f32_i32_e32 v81, v81
	v_cvt_f32_i32_e32 v80, v80
	v_cvt_f32_i32_e32 v78, v78
	v_cvt_f32_i32_e32 v75, v75
	v_cvt_f32_i32_e32 v77, v77
	v_cvt_f32_i32_e32 v76, v76
	v_cvt_f32_i32_e32 v74, v74
	v_cvt_f32_i32_e32 v71, v71
	v_cvt_f32_i32_e32 v70, v70
	v_cvt_f32_i32_e32 v67, v67
	v_cvt_f32_i32_e32 v69, v69
	v_cvt_f32_i32_e32 v68, v68
	v_cvt_f32_i32_e32 v66, v66
	v_cvt_f32_i32_e32 v73, v73
	v_cvt_f32_i32_e32 v72, v72
	v_lshlrev_b64 v[82:83], 13, v[82:83]
	v_lshl_add_u64 v[82:83], s[36:37], 0, v[82:83]
	v_pk_mul_f32 v[80:81], v[124:125], v[80:81]
	v_pk_mul_f32 v[78:79], v[122:123], v[78:79]
	v_pk_mul_f32 v[76:77], v[116:117], v[76:77]
	v_pk_mul_f32 v[74:75], v[114:115], v[74:75]
	v_lshl_add_u64 v[82:83], v[160:161], 1, v[82:83]
	v_pk_mul_f32 v[80:81], v[80:81], v[98:99] op_sel_hi:[1,0]
	v_pk_mul_f32 v[78:79], v[78:79], v[98:99] op_sel_hi:[1,0]
	v_pk_mul_f32 v[84:85], v[76:77], v[98:99] op_sel_hi:[1,0]
	v_pk_mul_f32 v[76:77], v[74:75], v[98:99] op_sel_hi:[1,0]
	v_cvt_pk_bf16_f32 v74, v78, v79
	v_cvt_pk_bf16_f32 v75, v80, v81
	v_pk_mul_f32 v[70:71], v[110:111], v[70:71]
	v_pk_mul_f32 v[68:69], v[108:109], v[68:69]
	v_pk_mul_f32 v[66:67], v[106:107], v[66:67]
	v_cvt_pk_bf16_f32 v76, v76, v77
	v_cvt_pk_bf16_f32 v77, v84, v85
	global_store_dwordx4 v[82:83], v[74:77], off
	v_pk_mul_f32 v[72:73], v[112:113], v[72:73]
	v_pk_mul_f32 v[70:71], v[70:71], v[98:99] op_sel_hi:[1,0]
	v_pk_mul_f32 v[74:75], v[68:69], v[98:99] op_sel_hi:[1,0]
	v_pk_mul_f32 v[68:69], v[66:67], v[98:99] op_sel_hi:[1,0]
	v_pk_mul_f32 v[72:73], v[72:73], v[98:99] op_sel_hi:[1,0]
	v_cvt_pk_bf16_f32 v66, v70, v71
	v_add_u32_e32 v70, 0x80, v162
	v_cvt_pk_bf16_f32 v67, v72, v73
	v_cvt_pk_bf16_f32 v68, v68, v69
	v_cvt_pk_bf16_f32 v69, v74, v75
	global_store_dwordx4 v[82:83], v[66:69], off offset:256
	v_ashrrev_i32_e32 v71, 31, v70
	s_and_b64 vcc, exec, s[6:7]
	v_mov_b32_e32 v66, 0x39010204
	v_mov_b32_e32 v68, 0x39010204
	s_cbranch_vccnz .LBB0_375
	v_mul_f32_e32 v68, 0x39010204, v203
.LBB0_375:
	v_cvt_f32_i32_e32 v63, v63
	v_cvt_f32_i32_e32 v65, v65
	v_cvt_f32_i32_e32 v64, v64
	v_cvt_f32_i32_e32 v62, v62
	v_cvt_f32_i32_e32 v59, v59
	v_cvt_f32_i32_e32 v61, v61
	v_cvt_f32_i32_e32 v60, v60
	v_cvt_f32_i32_e32 v58, v58
	v_cvt_f32_i32_e32 v55, v55
	v_cvt_f32_i32_e32 v54, v54
	v_cvt_f32_i32_e32 v51, v51
	v_cvt_f32_i32_e32 v53, v53
	v_cvt_f32_i32_e32 v52, v52
	v_cvt_f32_i32_e32 v50, v50
	v_cvt_f32_i32_e32 v57, v57
	v_cvt_f32_i32_e32 v56, v56
	v_lshlrev_b64 v[70:71], 13, v[70:71]
	v_lshl_add_u64 v[70:71], s[36:37], 0, v[70:71]
	v_pk_mul_f32 v[64:65], v[124:125], v[64:65]
	v_pk_mul_f32 v[62:63], v[122:123], v[62:63]
	v_pk_mul_f32 v[60:61], v[116:117], v[60:61]
	v_pk_mul_f32 v[58:59], v[114:115], v[58:59]
	v_lshl_add_u64 v[70:71], v[160:161], 1, v[70:71]
	v_pk_mul_f32 v[64:65], v[64:65], v[68:69] op_sel_hi:[1,0]
	v_pk_mul_f32 v[62:63], v[62:63], v[68:69] op_sel_hi:[1,0]
	v_pk_mul_f32 v[72:73], v[60:61], v[68:69] op_sel_hi:[1,0]
	v_pk_mul_f32 v[60:61], v[58:59], v[68:69] op_sel_hi:[1,0]
	v_cvt_pk_bf16_f32 v58, v62, v63
	v_cvt_pk_bf16_f32 v59, v64, v65
	v_pk_mul_f32 v[54:55], v[110:111], v[54:55]
	v_pk_mul_f32 v[52:53], v[108:109], v[52:53]
	v_pk_mul_f32 v[50:51], v[106:107], v[50:51]
	v_cvt_pk_bf16_f32 v60, v60, v61
	v_cvt_pk_bf16_f32 v61, v72, v73
	global_store_dwordx4 v[70:71], v[58:61], off
	v_pk_mul_f32 v[56:57], v[112:113], v[56:57]
	v_pk_mul_f32 v[54:55], v[54:55], v[68:69] op_sel_hi:[1,0]
	v_pk_mul_f32 v[58:59], v[52:53], v[68:69] op_sel_hi:[1,0]
	v_pk_mul_f32 v[52:53], v[50:51], v[68:69] op_sel_hi:[1,0]
	v_cvt_pk_bf16_f32 v50, v54, v55
	v_pk_mul_f32 v[56:57], v[56:57], v[68:69] op_sel_hi:[1,0]
	s_and_b64 vcc, exec, s[6:7]
	v_cvt_pk_bf16_f32 v51, v56, v57
	v_cvt_pk_bf16_f32 v52, v52, v53
	v_cvt_pk_bf16_f32 v53, v58, v59
	global_store_dwordx4 v[70:71], v[50:53], off offset:256
	s_nop 1
	v_add_u32_e32 v50, 0x90, v162
	v_ashrrev_i32_e32 v51, 31, v50
	s_cbranch_vccnz .LBB0_377
	v_mul_f32_e32 v66, 0x39010204, v204
.LBB0_377:
	v_cvt_f32_i32_e32 v47, v47
	v_cvt_f32_i32_e32 v49, v49
	v_cvt_f32_i32_e32 v48, v48
	v_cvt_f32_i32_e32 v46, v46
	v_cvt_f32_i32_e32 v43, v43
	v_cvt_f32_i32_e32 v45, v45
	v_cvt_f32_i32_e32 v44, v44
	v_cvt_f32_i32_e32 v42, v42
	v_cvt_f32_i32_e32 v39, v39
	v_cvt_f32_i32_e32 v38, v38
	v_cvt_f32_i32_e32 v35, v35
	v_cvt_f32_i32_e32 v37, v37
	v_cvt_f32_i32_e32 v36, v36
	v_cvt_f32_i32_e32 v34, v34
	v_cvt_f32_i32_e32 v41, v41
	v_cvt_f32_i32_e32 v40, v40
	v_lshlrev_b64 v[50:51], 13, v[50:51]
	v_lshl_add_u64 v[50:51], s[36:37], 0, v[50:51]
	v_pk_mul_f32 v[48:49], v[124:125], v[48:49]
	v_pk_mul_f32 v[46:47], v[122:123], v[46:47]
	v_pk_mul_f32 v[44:45], v[116:117], v[44:45]
	v_pk_mul_f32 v[42:43], v[114:115], v[42:43]
	v_lshl_add_u64 v[50:51], v[160:161], 1, v[50:51]
	v_pk_mul_f32 v[48:49], v[48:49], v[66:67] op_sel_hi:[1,0]
	v_pk_mul_f32 v[46:47], v[46:47], v[66:67] op_sel_hi:[1,0]
	v_pk_mul_f32 v[52:53], v[44:45], v[66:67] op_sel_hi:[1,0]
	v_pk_mul_f32 v[44:45], v[42:43], v[66:67] op_sel_hi:[1,0]
	v_cvt_pk_bf16_f32 v42, v46, v47
	v_cvt_pk_bf16_f32 v43, v48, v49
	v_pk_mul_f32 v[38:39], v[110:111], v[38:39]
	v_pk_mul_f32 v[36:37], v[108:109], v[36:37]
	v_pk_mul_f32 v[34:35], v[106:107], v[34:35]
	v_cvt_pk_bf16_f32 v44, v44, v45
	v_cvt_pk_bf16_f32 v45, v52, v53
	global_store_dwordx4 v[50:51], v[42:45], off
	v_pk_mul_f32 v[40:41], v[112:113], v[40:41]
	v_pk_mul_f32 v[38:39], v[38:39], v[66:67] op_sel_hi:[1,0]
	v_pk_mul_f32 v[42:43], v[36:37], v[66:67] op_sel_hi:[1,0]
	v_pk_mul_f32 v[36:37], v[34:35], v[66:67] op_sel_hi:[1,0]
	v_pk_mul_f32 v[40:41], v[40:41], v[66:67] op_sel_hi:[1,0]
	v_cvt_pk_bf16_f32 v34, v38, v39
	v_add_u32_e32 v38, 0xa0, v162
	v_cvt_pk_bf16_f32 v35, v40, v41
	v_cvt_pk_bf16_f32 v36, v36, v37
	v_cvt_pk_bf16_f32 v37, v42, v43
	global_store_dwordx4 v[50:51], v[34:37], off offset:256
	v_ashrrev_i32_e32 v39, 31, v38
	s_and_b64 vcc, exec, s[6:7]
	v_mov_b32_e32 v34, 0x39010204
	v_mov_b32_e32 v36, 0x39010204
	s_cbranch_vccnz .LBB0_379
	v_mul_f32_e32 v36, 0x39010204, v205
.LBB0_379:
	v_cvt_f32_i32_e32 v31, v31
	v_cvt_f32_i32_e32 v33, v33
	v_cvt_f32_i32_e32 v32, v32
	v_cvt_f32_i32_e32 v30, v30
	v_cvt_f32_i32_e32 v27, v27
	v_cvt_f32_i32_e32 v29, v29
	v_cvt_f32_i32_e32 v28, v28
	v_cvt_f32_i32_e32 v26, v26
	v_cvt_f32_i32_e32 v23, v23
	v_cvt_f32_i32_e32 v22, v22
	v_cvt_f32_i32_e32 v19, v19
	v_cvt_f32_i32_e32 v21, v21
	v_cvt_f32_i32_e32 v20, v20
	v_cvt_f32_i32_e32 v18, v18
	v_cvt_f32_i32_e32 v25, v25
	v_cvt_f32_i32_e32 v24, v24
	v_lshlrev_b64 v[38:39], 13, v[38:39]
	v_lshl_add_u64 v[38:39], s[36:37], 0, v[38:39]
	v_pk_mul_f32 v[32:33], v[124:125], v[32:33]
	v_pk_mul_f32 v[30:31], v[122:123], v[30:31]
	v_pk_mul_f32 v[28:29], v[116:117], v[28:29]
	v_pk_mul_f32 v[26:27], v[114:115], v[26:27]
	v_lshl_add_u64 v[38:39], v[160:161], 1, v[38:39]
	v_pk_mul_f32 v[32:33], v[32:33], v[36:37] op_sel_hi:[1,0]
	v_pk_mul_f32 v[30:31], v[30:31], v[36:37] op_sel_hi:[1,0]
	v_pk_mul_f32 v[40:41], v[28:29], v[36:37] op_sel_hi:[1,0]
	v_pk_mul_f32 v[28:29], v[26:27], v[36:37] op_sel_hi:[1,0]
	v_cvt_pk_bf16_f32 v26, v30, v31
	v_cvt_pk_bf16_f32 v27, v32, v33
	v_pk_mul_f32 v[22:23], v[110:111], v[22:23]
	v_pk_mul_f32 v[20:21], v[108:109], v[20:21]
	v_pk_mul_f32 v[18:19], v[106:107], v[18:19]
	v_cvt_pk_bf16_f32 v28, v28, v29
	v_cvt_pk_bf16_f32 v29, v40, v41
	global_store_dwordx4 v[38:39], v[26:29], off
	v_pk_mul_f32 v[24:25], v[112:113], v[24:25]
	v_pk_mul_f32 v[22:23], v[22:23], v[36:37] op_sel_hi:[1,0]
	v_pk_mul_f32 v[26:27], v[20:21], v[36:37] op_sel_hi:[1,0]
	v_pk_mul_f32 v[20:21], v[18:19], v[36:37] op_sel_hi:[1,0]
	v_cvt_pk_bf16_f32 v18, v22, v23
	v_pk_mul_f32 v[24:25], v[24:25], v[36:37] op_sel_hi:[1,0]
	s_and_b64 vcc, exec, s[6:7]
	v_cvt_pk_bf16_f32 v19, v24, v25
	v_cvt_pk_bf16_f32 v20, v20, v21
	v_cvt_pk_bf16_f32 v21, v26, v27
	global_store_dwordx4 v[38:39], v[18:21], off offset:256
	s_nop 1
	v_add_u32_e32 v18, 0xb0, v162
	v_ashrrev_i32_e32 v19, 31, v18
	s_cbranch_vccnz .LBB0_381
	v_mul_f32_e32 v34, 0x39010204, v206

.LBB0_544:
	v_lshl_add_u32 v146, s4, 8, v1
	v_cndmask_b32_e64 v148, 0, 1, s[44:45]
	v_ashrrev_i32_e32 v147, 31, v146
	v_mov_b32_e32 v150, 1.0
	v_cmp_ne_u32_e64 s[4:5], 1, v148
	s_andn2_b64 vcc, exec, s[44:45]
	v_mov_b32_e32 v152, 1.0
	s_cbranch_vccnz .LBB0_546
	v_lshl_add_u64 v[148:149], v[146:147], 2, s[70:71]
	global_load_dword v152, v[148:149], off
	global_load_dword v200, v[148:149], off offset:64
	global_load_dword v201, v[148:149], off offset:128
	global_load_dword v202, v[148:149], off offset:192
	global_load_dword v203, v[148:149], off offset:512
	global_load_dword v204, v[148:149], off offset:576
	global_load_dword v205, v[148:149], off offset:640
	global_load_dword v206, v[148:149], off offset:704
.LBB0_546:
	v_lshl_or_b32 v148, s82, 8, v153
	v_mov_b64_e32 v[158:159], s[38:39]
	v_ashrrev_i32_e32 v149, 31, v148
	v_mad_i64_i32 v[158:159], s[8:9], v146, s91, v[158:159]
	v_lshl_add_u64 v[158:159], v[148:149], 1, v[158:159]
	s_waitcnt vmcnt(0)
	v_pk_mul_f32 v[128:129], v[128:129], v[152:153] op_sel_hi:[1,0]
	v_pk_mul_f32 v[126:127], v[126:127], v[152:153] op_sel_hi:[1,0]
	v_pk_mul_f32 v[160:161], v[124:125], v[152:153] op_sel_hi:[1,0]
	v_pk_mul_f32 v[124:125], v[122:123], v[152:153] op_sel_hi:[1,0]
	v_cvt_pk_bf16_f32 v122, v126, v127
	v_cvt_pk_bf16_f32 v123, v128, v129
	v_pk_mul_f32 v[118:119], v[118:119], v[152:153] op_sel_hi:[1,0]
	v_cvt_pk_bf16_f32 v124, v124, v125
	v_cvt_pk_bf16_f32 v125, v160, v161
	global_store_dwordx4 v[158:159], v[122:125], off
	v_pk_mul_f32 v[120:121], v[120:121], v[152:153] op_sel_hi:[1,0]
	s_and_b64 vcc, exec, s[4:5]
	v_pk_mul_f32 v[122:123], v[116:117], v[152:153] op_sel_hi:[1,0]
	v_pk_mul_f32 v[116:117], v[114:115], v[152:153] op_sel_hi:[1,0]
	v_cvt_pk_bf16_f32 v114, v118, v119
	v_cvt_pk_bf16_f32 v115, v120, v121
	s_nop 0
	v_cvt_pk_bf16_f32 v116, v116, v117
	v_cvt_pk_bf16_f32 v117, v122, v123
	global_store_dwordx4 v[158:159], v[114:117], off offset:256
	s_nop 1
	v_or_b32_e32 v114, 16, v146
	v_ashrrev_i32_e32 v115, 31, v114
	s_cbranch_vccnz .LBB0_548
	v_mov_b32_e32 v150, v200
.LBB0_548:
	v_mov_b64_e32 v[116:117], s[38:39]
	v_mad_i64_i32 v[114:115], s[8:9], v114, s91, v[116:117]
	v_lshl_add_u64 v[114:115], v[148:149], 1, v[114:115]
	v_pk_mul_f32 v[112:113], v[112:113], v[150:151] op_sel_hi:[1,0]
	v_pk_mul_f32 v[110:111], v[110:111], v[150:151] op_sel_hi:[1,0]
	v_pk_mul_f32 v[116:117], v[108:109], v[150:151] op_sel_hi:[1,0]
	v_pk_mul_f32 v[108:109], v[106:107], v[150:151] op_sel_hi:[1,0]
	v_cvt_pk_bf16_f32 v106, v110, v111
	v_cvt_pk_bf16_f32 v107, v112, v113
	v_pk_mul_f32 v[102:103], v[102:103], v[150:151] op_sel_hi:[1,0]
	v_cvt_pk_bf16_f32 v108, v108, v109
	v_cvt_pk_bf16_f32 v109, v116, v117
	global_store_dwordx4 v[114:115], v[106:109], off
	v_pk_mul_f32 v[104:105], v[104:105], v[150:151] op_sel_hi:[1,0]
	s_and_b64 vcc, exec, s[4:5]
	v_pk_mul_f32 v[106:107], v[100:101], v[150:151] op_sel_hi:[1,0]
	v_pk_mul_f32 v[100:101], v[98:99], v[150:151] op_sel_hi:[1,0]
	v_cvt_pk_bf16_f32 v98, v102, v103
	v_cvt_pk_bf16_f32 v99, v104, v105
	v_or_b32_e32 v102, 32, v146
	v_cvt_pk_bf16_f32 v100, v100, v101
	v_cvt_pk_bf16_f32 v101, v106, v107
	global_store_dwordx4 v[114:115], v[98:101], off offset:256
	v_ashrrev_i32_e32 v103, 31, v102
	s_nop 0
	v_mov_b32_e32 v98, 1.0
	v_mov_b32_e32 v100, 1.0
	s_cbranch_vccnz .LBB0_550
	v_mov_b32_e32 v100, v201
.LBB0_550:
	v_mov_b64_e32 v[104:105], s[38:39]
	v_mad_i64_i32 v[102:103], s[8:9], v102, s91, v[104:105]
	v_lshl_add_u64 v[102:103], v[148:149], 1, v[102:103]
	v_pk_mul_f32 v[96:97], v[96:97], v[100:101] op_sel_hi:[1,0]
	v_pk_mul_f32 v[94:95], v[94:95], v[100:101] op_sel_hi:[1,0]
	v_pk_mul_f32 v[104:105], v[92:93], v[100:101] op_sel_hi:[1,0]
	v_pk_mul_f32 v[92:93], v[90:91], v[100:101] op_sel_hi:[1,0]
	v_cvt_pk_bf16_f32 v90, v94, v95
	v_cvt_pk_bf16_f32 v91, v96, v97
	v_pk_mul_f32 v[86:87], v[86:87], v[100:101] op_sel_hi:[1,0]
	v_cvt_pk_bf16_f32 v92, v92, v93
	v_cvt_pk_bf16_f32 v93, v104, v105
	global_store_dwordx4 v[102:103], v[90:93], off
	v_pk_mul_f32 v[88:89], v[88:89], v[100:101] op_sel_hi:[1,0]
	s_and_b64 vcc, exec, s[4:5]
	v_pk_mul_f32 v[90:91], v[84:85], v[100:101] op_sel_hi:[1,0]
	v_pk_mul_f32 v[84:85], v[82:83], v[100:101] op_sel_hi:[1,0]
	v_cvt_pk_bf16_f32 v82, v86, v87
	v_cvt_pk_bf16_f32 v83, v88, v89
	s_nop 0
	v_cvt_pk_bf16_f32 v84, v84, v85
	v_cvt_pk_bf16_f32 v85, v90, v91
	global_store_dwordx4 v[102:103], v[82:85], off offset:256
	s_nop 1
	v_or_b32_e32 v82, 48, v146
	v_ashrrev_i32_e32 v83, 31, v82
	s_cbranch_vccnz .LBB0_552
	v_mov_b32_e32 v98, v202
.LBB0_552:
	v_mov_b64_e32 v[84:85], s[38:39]
	v_mad_i64_i32 v[82:83], s[8:9], v82, s91, v[84:85]
	v_lshl_add_u64 v[82:83], v[148:149], 1, v[82:83]
	v_pk_mul_f32 v[80:81], v[80:81], v[98:99] op_sel_hi:[1,0]
	v_pk_mul_f32 v[78:79], v[78:79], v[98:99] op_sel_hi:[1,0]
	v_pk_mul_f32 v[84:85], v[76:77], v[98:99] op_sel_hi:[1,0]
	v_pk_mul_f32 v[76:77], v[74:75], v[98:99] op_sel_hi:[1,0]
	v_cvt_pk_bf16_f32 v74, v78, v79
	v_cvt_pk_bf16_f32 v75, v80, v81
	v_pk_mul_f32 v[70:71], v[70:71], v[98:99] op_sel_hi:[1,0]
	v_cvt_pk_bf16_f32 v76, v76, v77
	v_cvt_pk_bf16_f32 v77, v84, v85
	global_store_dwordx4 v[82:83], v[74:77], off
	v_pk_mul_f32 v[72:73], v[72:73], v[98:99] op_sel_hi:[1,0]
	s_and_b64 vcc, exec, s[4:5]
	v_pk_mul_f32 v[74:75], v[68:69], v[98:99] op_sel_hi:[1,0]
	v_pk_mul_f32 v[68:69], v[66:67], v[98:99] op_sel_hi:[1,0]
	v_cvt_pk_bf16_f32 v66, v70, v71
	v_cvt_pk_bf16_f32 v67, v72, v73
	v_add_u32_e32 v70, 0x80, v146
	v_cvt_pk_bf16_f32 v68, v68, v69
	v_cvt_pk_bf16_f32 v69, v74, v75
	global_store_dwordx4 v[82:83], v[66:69], off offset:256
	v_ashrrev_i32_e32 v71, 31, v70
	s_nop 0
	v_mov_b32_e32 v66, 1.0
	v_mov_b32_e32 v68, 1.0
	s_cbranch_vccnz .LBB0_554
	v_mov_b32_e32 v68, v203
.LBB0_554:
	v_mov_b64_e32 v[72:73], s[38:39]
	v_mad_i64_i32 v[70:71], s[8:9], v70, s91, v[72:73]
	v_lshl_add_u64 v[70:71], v[148:149], 1, v[70:71]
	v_pk_mul_f32 v[64:65], v[64:65], v[68:69] op_sel_hi:[1,0]
	v_pk_mul_f32 v[62:63], v[62:63], v[68:69] op_sel_hi:[1,0]
	v_pk_mul_f32 v[72:73], v[60:61], v[68:69] op_sel_hi:[1,0]
	v_pk_mul_f32 v[60:61], v[58:59], v[68:69] op_sel_hi:[1,0]
	v_cvt_pk_bf16_f32 v58, v62, v63
	v_cvt_pk_bf16_f32 v59, v64, v65
	v_pk_mul_f32 v[54:55], v[54:55], v[68:69] op_sel_hi:[1,0]
	v_cvt_pk_bf16_f32 v60, v60, v61
	v_cvt_pk_bf16_f32 v61, v72, v73
	global_store_dwordx4 v[70:71], v[58:61], off
	v_pk_mul_f32 v[56:57], v[56:57], v[68:69] op_sel_hi:[1,0]
	s_and_b64 vcc, exec, s[4:5]
	v_pk_mul_f32 v[58:59], v[52:53], v[68:69] op_sel_hi:[1,0]
	v_pk_mul_f32 v[52:53], v[50:51], v[68:69] op_sel_hi:[1,0]
	v_cvt_pk_bf16_f32 v50, v54, v55
	v_cvt_pk_bf16_f32 v51, v56, v57
	s_nop 0
	v_cvt_pk_bf16_f32 v52, v52, v53
	v_cvt_pk_bf16_f32 v53, v58, v59
	global_store_dwordx4 v[70:71], v[50:53], off offset:256
	s_nop 1
	v_add_u32_e32 v50, 0x90, v146
	v_ashrrev_i32_e32 v51, 31, v50
	s_cbranch_vccnz .LBB0_556
	v_mov_b32_e32 v66, v204
.LBB0_556:
	v_mov_b64_e32 v[52:53], s[38:39]
	v_mad_i64_i32 v[50:51], s[8:9], v50, s91, v[52:53]
	v_lshl_add_u64 v[50:51], v[148:149], 1, v[50:51]
	v_pk_mul_f32 v[48:49], v[48:49], v[66:67] op_sel_hi:[1,0]
	v_pk_mul_f32 v[46:47], v[46:47], v[66:67] op_sel_hi:[1,0]
	v_pk_mul_f32 v[52:53], v[44:45], v[66:67] op_sel_hi:[1,0]
	v_pk_mul_f32 v[44:45], v[42:43], v[66:67] op_sel_hi:[1,0]
	v_cvt_pk_bf16_f32 v42, v46, v47
	v_cvt_pk_bf16_f32 v43, v48, v49
	v_pk_mul_f32 v[38:39], v[38:39], v[66:67] op_sel_hi:[1,0]
	v_cvt_pk_bf16_f32 v44, v44, v45
	v_cvt_pk_bf16_f32 v45, v52, v53
	global_store_dwordx4 v[50:51], v[42:45], off
	v_pk_mul_f32 v[40:41], v[40:41], v[66:67] op_sel_hi:[1,0]
	s_and_b64 vcc, exec, s[4:5]
	v_pk_mul_f32 v[42:43], v[36:37], v[66:67] op_sel_hi:[1,0]
	v_pk_mul_f32 v[36:37], v[34:35], v[66:67] op_sel_hi:[1,0]
	v_cvt_pk_bf16_f32 v34, v38, v39
	v_cvt_pk_bf16_f32 v35, v40, v41
	v_add_u32_e32 v38, 0xa0, v146
	v_cvt_pk_bf16_f32 v36, v36, v37
	v_cvt_pk_bf16_f32 v37, v42, v43
	global_store_dwordx4 v[50:51], v[34:37], off offset:256
	v_ashrrev_i32_e32 v39, 31, v38
	s_nop 0
	v_mov_b32_e32 v34, 1.0
	v_mov_b32_e32 v36, 1.0
	s_cbranch_vccnz .LBB0_558
	v_mov_b32_e32 v36, v205
.LBB0_558:
	v_mov_b64_e32 v[40:41], s[38:39]
	v_mad_i64_i32 v[38:39], s[8:9], v38, s91, v[40:41]
	v_lshl_add_u64 v[38:39], v[148:149], 1, v[38:39]
	v_pk_mul_f32 v[32:33], v[32:33], v[36:37] op_sel_hi:[1,0]
	v_pk_mul_f32 v[30:31], v[30:31], v[36:37] op_sel_hi:[1,0]
	v_pk_mul_f32 v[40:41], v[28:29], v[36:37] op_sel_hi:[1,0]
	v_pk_mul_f32 v[28:29], v[26:27], v[36:37] op_sel_hi:[1,0]
	v_cvt_pk_bf16_f32 v26, v30, v31
	v_cvt_pk_bf16_f32 v27, v32, v33
	v_pk_mul_f32 v[22:23], v[22:23], v[36:37] op_sel_hi:[1,0]
	v_cvt_pk_bf16_f32 v28, v28, v29
	v_cvt_pk_bf16_f32 v29, v40, v41
	global_store_dwordx4 v[38:39], v[26:29], off
	v_pk_mul_f32 v[24:25], v[24:25], v[36:37] op_sel_hi:[1,0]
	s_and_b64 vcc, exec, s[4:5]
	v_pk_mul_f32 v[26:27], v[20:21], v[36:37] op_sel_hi:[1,0]
	v_pk_mul_f32 v[20:21], v[18:19], v[36:37] op_sel_hi:[1,0]
	v_cvt_pk_bf16_f32 v18, v22, v23
	v_cvt_pk_bf16_f32 v19, v24, v25
	s_nop 0
	v_cvt_pk_bf16_f32 v20, v20, v21
	v_cvt_pk_bf16_f32 v21, v26, v27
	global_store_dwordx4 v[38:39], v[18:21], off offset:256
	s_nop 1
	v_add_u32_e32 v18, 0xb0, v146
	v_ashrrev_i32_e32 v19, 31, v18
	s_cbranch_vccnz .LBB0_560
	v_mov_b32_e32 v34, v206
.LBB0_560:
	v_mov_b64_e32 v[20:21], s[38:39]
	v_mad_i64_i32 v[18:19], s[4:5], v18, s91, v[20:21]
	v_lshl_add_u64 v[18:19], v[148:149], 1, v[18:19]
	v_pk_mul_f32 v[16:17], v[16:17], v[34:35] op_sel_hi:[1,0]
	v_pk_mul_f32 v[14:15], v[14:15], v[34:35] op_sel_hi:[1,0]
	v_pk_mul_f32 v[20:21], v[12:13], v[34:35] op_sel_hi:[1,0]
	v_pk_mul_f32 v[12:13], v[10:11], v[34:35] op_sel_hi:[1,0]
	v_cvt_pk_bf16_f32 v10, v14, v15
	v_cvt_pk_bf16_f32 v11, v16, v17
	s_andn2_b64 vcc, exec, s[2:3]
	v_cvt_pk_bf16_f32 v12, v12, v13
	v_cvt_pk_bf16_f32 v13, v20, v21
	global_store_dwordx4 v[18:19], v[10:13], off
	s_mov_b64 s[2:3], -1
	v_pk_mul_f32 v[8:9], v[8:9], v[34:35] op_sel_hi:[1,0]
	v_pk_mul_f32 v[10:11], v[4:5], v[34:35] op_sel_hi:[1,0]
	v_pk_mul_f32 v[4:5], v[2:3], v[34:35] op_sel_hi:[1,0]
	v_pk_mul_f32 v[6:7], v[6:7], v[34:35] op_sel_hi:[1,0]
	s_nop 0
	v_cvt_pk_bf16_f32 v2, v6, v7
	v_cvt_pk_bf16_f32 v3, v8, v9
	v_cvt_pk_bf16_f32 v4, v4, v5
	v_cvt_pk_bf16_f32 v5, v10, v11
	global_store_dwordx4 v[18:19], v[2:5], off offset:256
	s_cbranch_vccnz .LBB0_537
	s_andn2_b64 vcc, exec, s[0:1]
	s_cbranch_vccnz .LBB0_536
	s_barrier
	s_branch .LBB0_536

.LBB0_1169:
	v_lshl_or_b32 v158, s54, 8, v166
	v_ashrrev_i32_e32 v159, 31, v158
	v_lshl_add_u64 v[108:109], v[158:159], 2, s[12:13]
	global_load_dwordx4 v[112:115], v[108:109], off offset:16
	global_load_dwordx4 v[120:123], v[108:109], off
	global_load_dwordx4 v[104:107], v[108:109], off offset:528
	s_nop 0
	global_load_dwordx4 v[108:111], v[108:109], off offset:512
	v_lshl_add_u32 v160, s53, 8, v163
	v_cndmask_b32_e64 v164, 0, 1, s[20:21]
	v_ashrrev_i32_e32 v161, 31, v160
	v_mov_b32_e32 v162, 0x39010204
	v_cmp_ne_u32_e64 s[6:7], 1, v164
	s_andn2_b64 vcc, exec, s[20:21]
	v_mov_b32_e32 v164, 0x39010204
	s_cbranch_vccnz .LBB0_1171
	v_lshl_add_u64 v[170:171], v[160:161], 2, s[70:71]
	global_load_dword v164, v[170:171], off
	global_load_dword v200, v[170:171], off offset:64
	global_load_dword v201, v[170:171], off offset:128
	global_load_dword v202, v[170:171], off offset:192
	global_load_dword v203, v[170:171], off offset:512
	global_load_dword v204, v[170:171], off offset:576
	global_load_dword v205, v[170:171], off offset:640
	global_load_dword v206, v[170:171], off offset:704
	s_waitcnt vmcnt(0)
	v_mul_f32_e32 v164, 0x39010204, v164
.LBB0_1171:
	v_cvt_f32_i32_e32 v141, v141
	v_cvt_f32_i32_e32 v143, v143
	v_cvt_f32_i32_e32 v142, v142
	v_cvt_f32_i32_e32 v140, v140
	v_cvt_f32_i32_e32 v139, v139
	v_cvt_f32_i32_e32 v137, v137
	v_cvt_f32_i32_e32 v136, v136
	v_cvt_f32_i32_e32 v138, v138
	v_cvt_f32_i32_e32 v133, v133
	v_cvt_f32_i32_e32 v132, v132
	v_cvt_f32_i32_e32 v131, v131
	v_cvt_f32_i32_e32 v129, v129
	v_cvt_f32_i32_e32 v128, v128
	v_cvt_f32_i32_e32 v130, v130
	v_cvt_f32_i32_e32 v135, v135
	v_cvt_f32_i32_e32 v134, v134
	v_lshlrev_b64 v[170:171], 13, v[160:161]
	v_lshl_add_u64 v[170:171], s[36:37], 0, v[170:171]
	s_waitcnt vmcnt(0)
	v_pk_mul_f32 v[142:143], v[122:123], v[142:143]
	v_pk_mul_f32 v[140:141], v[120:121], v[140:141]
	v_pk_mul_f32 v[136:137], v[112:113], v[136:137]
	v_pk_mul_f32 v[138:139], v[114:115], v[138:139]
	v_lshl_add_u64 v[170:171], v[158:159], 1, v[170:171]
	v_pk_mul_f32 v[142:143], v[142:143], v[164:165] op_sel_hi:[1,0]
	v_pk_mul_f32 v[140:141], v[140:141], v[164:165] op_sel_hi:[1,0]
	v_pk_mul_f32 v[172:173], v[138:139], v[164:165] op_sel_hi:[1,0]
	v_pk_mul_f32 v[138:139], v[136:137], v[164:165] op_sel_hi:[1,0]
	v_cvt_pk_bf16_f32 v136, v140, v141
	v_cvt_pk_bf16_f32 v137, v142, v143
	v_pk_mul_f32 v[132:133], v[108:109], v[132:133]
	v_pk_mul_f32 v[128:129], v[104:105], v[128:129]
	v_pk_mul_f32 v[130:131], v[106:107], v[130:131]
	v_cvt_pk_bf16_f32 v138, v138, v139
	v_cvt_pk_bf16_f32 v139, v172, v173
	global_store_dwordx4 v[170:171], v[136:139], off
	v_pk_mul_f32 v[134:135], v[110:111], v[134:135]
	v_pk_mul_f32 v[132:133], v[132:133], v[164:165] op_sel_hi:[1,0]
	v_pk_mul_f32 v[136:137], v[130:131], v[164:165] op_sel_hi:[1,0]
	v_pk_mul_f32 v[130:131], v[128:129], v[164:165] op_sel_hi:[1,0]
	v_cvt_pk_bf16_f32 v128, v132, v133
	v_pk_mul_f32 v[134:135], v[134:135], v[164:165] op_sel_hi:[1,0]
	s_and_b64 vcc, exec, s[6:7]
	v_cvt_pk_bf16_f32 v129, v134, v135
	v_cvt_pk_bf16_f32 v130, v130, v131
	v_cvt_pk_bf16_f32 v131, v136, v137
	global_store_dwordx4 v[170:171], v[128:131], off offset:256
	s_nop 1
	v_or_b32_e32 v128, 16, v160
	v_ashrrev_i32_e32 v129, 31, v128
	s_cbranch_vccnz .LBB0_1173
	v_mul_f32_e32 v162, 0x39010204, v200
.LBB0_1173:
	v_cvt_f32_i32_e32 v125, v125
	v_cvt_f32_i32_e32 v127, v127
	v_cvt_f32_i32_e32 v126, v126
	v_cvt_f32_i32_e32 v124, v124
	v_cvt_f32_i32_e32 v117, v117
	v_cvt_f32_i32_e32 v119, v119
	v_cvt_f32_i32_e32 v118, v118
	v_cvt_f32_i32_e32 v116, v116
	v_cvt_f32_i32_e32 v101, v101
	v_cvt_f32_i32_e32 v100, v100
	v_cvt_f32_i32_e32 v97, v97
	v_cvt_f32_i32_e32 v99, v99
	v_cvt_f32_i32_e32 v98, v98
	v_cvt_f32_i32_e32 v96, v96
	v_cvt_f32_i32_e32 v103, v103
	v_cvt_f32_i32_e32 v102, v102
	v_lshlrev_b64 v[128:129], 13, v[128:129]
	v_lshl_add_u64 v[128:129], s[36:37], 0, v[128:129]
	v_pk_mul_f32 v[126:127], v[122:123], v[126:127]
	v_pk_mul_f32 v[124:125], v[120:121], v[124:125]
	v_pk_mul_f32 v[118:119], v[114:115], v[118:119]
	v_pk_mul_f32 v[116:117], v[112:113], v[116:117]
	v_lshl_add_u64 v[128:129], v[158:159], 1, v[128:129]
	v_pk_mul_f32 v[126:127], v[126:127], v[162:163] op_sel_hi:[1,0]
	v_pk_mul_f32 v[124:125], v[124:125], v[162:163] op_sel_hi:[1,0]
	v_pk_mul_f32 v[130:131], v[118:119], v[162:163] op_sel_hi:[1,0]
	v_pk_mul_f32 v[118:119], v[116:117], v[162:163] op_sel_hi:[1,0]
	v_cvt_pk_bf16_f32 v116, v124, v125
	v_cvt_pk_bf16_f32 v117, v126, v127
	v_pk_mul_f32 v[100:101], v[108:109], v[100:101]
	v_pk_mul_f32 v[98:99], v[106:107], v[98:99]
	v_pk_mul_f32 v[96:97], v[104:105], v[96:97]
	v_cvt_pk_bf16_f32 v118, v118, v119
	v_cvt_pk_bf16_f32 v119, v130, v131
	global_store_dwordx4 v[128:129], v[116:119], off
	v_pk_mul_f32 v[102:103], v[110:111], v[102:103]
	v_pk_mul_f32 v[100:101], v[100:101], v[162:163] op_sel_hi:[1,0]
	v_pk_mul_f32 v[116:117], v[98:99], v[162:163] op_sel_hi:[1,0]
	v_pk_mul_f32 v[98:99], v[96:97], v[162:163] op_sel_hi:[1,0]
	v_pk_mul_f32 v[102:103], v[102:103], v[162:163] op_sel_hi:[1,0]
	v_cvt_pk_bf16_f32 v96, v100, v101
	v_or_b32_e32 v100, 32, v160
	v_cvt_pk_bf16_f32 v97, v102, v103
	v_cvt_pk_bf16_f32 v98, v98, v99
	v_cvt_pk_bf16_f32 v99, v116, v117
	global_store_dwordx4 v[128:129], v[96:99], off offset:256
	v_ashrrev_i32_e32 v101, 31, v100
	s_and_b64 vcc, exec, s[6:7]
	v_mov_b32_e32 v96, 0x39010204
	v_mov_b32_e32 v98, 0x39010204
	s_cbranch_vccnz .LBB0_1175
	v_mul_f32_e32 v98, 0x39010204, v201
.LBB0_1175:
	v_cvt_f32_i32_e32 v93, v93
	v_cvt_f32_i32_e32 v95, v95
	v_cvt_f32_i32_e32 v94, v94
	v_cvt_f32_i32_e32 v92, v92
	v_cvt_f32_i32_e32 v89, v89
	v_cvt_f32_i32_e32 v91, v91
	v_cvt_f32_i32_e32 v90, v90
	v_cvt_f32_i32_e32 v88, v88
	v_cvt_f32_i32_e32 v85, v85
	v_cvt_f32_i32_e32 v84, v84
	v_cvt_f32_i32_e32 v81, v81
	v_cvt_f32_i32_e32 v83, v83
	v_cvt_f32_i32_e32 v82, v82
	v_cvt_f32_i32_e32 v80, v80
	v_cvt_f32_i32_e32 v87, v87
	v_cvt_f32_i32_e32 v86, v86
	v_lshlrev_b64 v[100:101], 13, v[100:101]
	v_lshl_add_u64 v[100:101], s[36:37], 0, v[100:101]
	v_pk_mul_f32 v[94:95], v[122:123], v[94:95]
	v_pk_mul_f32 v[92:93], v[120:121], v[92:93]
	v_pk_mul_f32 v[90:91], v[114:115], v[90:91]
	v_pk_mul_f32 v[88:89], v[112:113], v[88:89]
	v_lshl_add_u64 v[100:101], v[158:159], 1, v[100:101]
	v_pk_mul_f32 v[94:95], v[94:95], v[98:99] op_sel_hi:[1,0]
	v_pk_mul_f32 v[92:93], v[92:93], v[98:99] op_sel_hi:[1,0]
	v_pk_mul_f32 v[102:103], v[90:91], v[98:99] op_sel_hi:[1,0]
	v_pk_mul_f32 v[90:91], v[88:89], v[98:99] op_sel_hi:[1,0]
	v_cvt_pk_bf16_f32 v88, v92, v93
	v_cvt_pk_bf16_f32 v89, v94, v95
	v_pk_mul_f32 v[84:85], v[108:109], v[84:85]
	v_pk_mul_f32 v[82:83], v[106:107], v[82:83]
	v_pk_mul_f32 v[80:81], v[104:105], v[80:81]
	v_cvt_pk_bf16_f32 v90, v90, v91
	v_cvt_pk_bf16_f32 v91, v102, v103
	global_store_dwordx4 v[100:101], v[88:91], off
	v_pk_mul_f32 v[86:87], v[110:111], v[86:87]
	v_pk_mul_f32 v[84:85], v[84:85], v[98:99] op_sel_hi:[1,0]
	v_pk_mul_f32 v[88:89], v[82:83], v[98:99] op_sel_hi:[1,0]
	v_pk_mul_f32 v[82:83], v[80:81], v[98:99] op_sel_hi:[1,0]
	v_cvt_pk_bf16_f32 v80, v84, v85
	v_pk_mul_f32 v[86:87], v[86:87], v[98:99] op_sel_hi:[1,0]
	s_and_b64 vcc, exec, s[6:7]
	v_cvt_pk_bf16_f32 v81, v86, v87
	v_cvt_pk_bf16_f32 v82, v82, v83
	v_cvt_pk_bf16_f32 v83, v88, v89
	global_store_dwordx4 v[100:101], v[80:83], off offset:256
	s_nop 1
	v_or_b32_e32 v80, 48, v160
	v_ashrrev_i32_e32 v81, 31, v80
	s_cbranch_vccnz .LBB0_1177
	v_mul_f32_e32 v96, 0x39010204, v202
.LBB0_1177:
	v_cvt_f32_i32_e32 v77, v77
	v_cvt_f32_i32_e32 v79, v79
	v_cvt_f32_i32_e32 v78, v78
	v_cvt_f32_i32_e32 v76, v76
	v_cvt_f32_i32_e32 v73, v73
	v_cvt_f32_i32_e32 v75, v75
	v_cvt_f32_i32_e32 v74, v74
	v_cvt_f32_i32_e32 v72, v72
	v_cvt_f32_i32_e32 v69, v69
	v_cvt_f32_i32_e32 v68, v68
	v_cvt_f32_i32_e32 v65, v65
	v_cvt_f32_i32_e32 v67, v67
	v_cvt_f32_i32_e32 v66, v66
	v_cvt_f32_i32_e32 v64, v64
	v_cvt_f32_i32_e32 v71, v71
	v_cvt_f32_i32_e32 v70, v70
	v_lshlrev_b64 v[80:81], 13, v[80:81]
	v_lshl_add_u64 v[80:81], s[36:37], 0, v[80:81]
	v_pk_mul_f32 v[78:79], v[122:123], v[78:79]
	v_pk_mul_f32 v[76:77], v[120:121], v[76:77]
	v_pk_mul_f32 v[74:75], v[114:115], v[74:75]
	v_pk_mul_f32 v[72:73], v[112:113], v[72:73]
	v_lshl_add_u64 v[80:81], v[158:159], 1, v[80:81]
	v_pk_mul_f32 v[78:79], v[78:79], v[96:97] op_sel_hi:[1,0]
	v_pk_mul_f32 v[76:77], v[76:77], v[96:97] op_sel_hi:[1,0]
	v_pk_mul_f32 v[82:83], v[74:75], v[96:97] op_sel_hi:[1,0]
	v_pk_mul_f32 v[74:75], v[72:73], v[96:97] op_sel_hi:[1,0]
	v_cvt_pk_bf16_f32 v72, v76, v77
	v_cvt_pk_bf16_f32 v73, v78, v79
	v_pk_mul_f32 v[68:69], v[108:109], v[68:69]
	v_pk_mul_f32 v[66:67], v[106:107], v[66:67]
	v_pk_mul_f32 v[64:65], v[104:105], v[64:65]
	v_cvt_pk_bf16_f32 v74, v74, v75
	v_cvt_pk_bf16_f32 v75, v82, v83
	global_store_dwordx4 v[80:81], v[72:75], off
	v_pk_mul_f32 v[70:71], v[110:111], v[70:71]
	v_pk_mul_f32 v[68:69], v[68:69], v[96:97] op_sel_hi:[1,0]
	v_pk_mul_f32 v[72:73], v[66:67], v[96:97] op_sel_hi:[1,0]
	v_pk_mul_f32 v[66:67], v[64:65], v[96:97] op_sel_hi:[1,0]
	v_pk_mul_f32 v[70:71], v[70:71], v[96:97] op_sel_hi:[1,0]
	v_cvt_pk_bf16_f32 v64, v68, v69
	v_add_u32_e32 v68, 0x80, v160
	v_cvt_pk_bf16_f32 v65, v70, v71
	v_cvt_pk_bf16_f32 v66, v66, v67
	v_cvt_pk_bf16_f32 v67, v72, v73
	global_store_dwordx4 v[80:81], v[64:67], off offset:256
	v_ashrrev_i32_e32 v69, 31, v68
	s_and_b64 vcc, exec, s[6:7]
	v_mov_b32_e32 v64, 0x39010204
	v_mov_b32_e32 v66, 0x39010204
	s_cbranch_vccnz .LBB0_1179
	v_mul_f32_e32 v66, 0x39010204, v203
.LBB0_1179:
	v_cvt_f32_i32_e32 v61, v61
	v_cvt_f32_i32_e32 v63, v63
	v_cvt_f32_i32_e32 v62, v62
	v_cvt_f32_i32_e32 v60, v60
	v_cvt_f32_i32_e32 v57, v57
	v_cvt_f32_i32_e32 v59, v59
	v_cvt_f32_i32_e32 v58, v58
	v_cvt_f32_i32_e32 v56, v56
	v_cvt_f32_i32_e32 v53, v53
	v_cvt_f32_i32_e32 v52, v52
	v_cvt_f32_i32_e32 v49, v49
	v_cvt_f32_i32_e32 v51, v51
	v_cvt_f32_i32_e32 v50, v50
	v_cvt_f32_i32_e32 v48, v48
	v_cvt_f32_i32_e32 v55, v55
	v_cvt_f32_i32_e32 v54, v54
	v_lshlrev_b64 v[68:69], 13, v[68:69]
	v_lshl_add_u64 v[68:69], s[36:37], 0, v[68:69]
	v_pk_mul_f32 v[62:63], v[122:123], v[62:63]
	v_pk_mul_f32 v[60:61], v[120:121], v[60:61]
	v_pk_mul_f32 v[58:59], v[114:115], v[58:59]
	v_pk_mul_f32 v[56:57], v[112:113], v[56:57]
	v_lshl_add_u64 v[68:69], v[158:159], 1, v[68:69]
	v_pk_mul_f32 v[62:63], v[62:63], v[66:67] op_sel_hi:[1,0]
	v_pk_mul_f32 v[60:61], v[60:61], v[66:67] op_sel_hi:[1,0]
	v_pk_mul_f32 v[70:71], v[58:59], v[66:67] op_sel_hi:[1,0]
	v_pk_mul_f32 v[58:59], v[56:57], v[66:67] op_sel_hi:[1,0]
	v_cvt_pk_bf16_f32 v56, v60, v61
	v_cvt_pk_bf16_f32 v57, v62, v63
	v_pk_mul_f32 v[52:53], v[108:109], v[52:53]
	v_pk_mul_f32 v[50:51], v[106:107], v[50:51]
	v_pk_mul_f32 v[48:49], v[104:105], v[48:49]
	v_cvt_pk_bf16_f32 v58, v58, v59
	v_cvt_pk_bf16_f32 v59, v70, v71
	global_store_dwordx4 v[68:69], v[56:59], off
	v_pk_mul_f32 v[54:55], v[110:111], v[54:55]
	v_pk_mul_f32 v[52:53], v[52:53], v[66:67] op_sel_hi:[1,0]
	v_pk_mul_f32 v[56:57], v[50:51], v[66:67] op_sel_hi:[1,0]
	v_pk_mul_f32 v[50:51], v[48:49], v[66:67] op_sel_hi:[1,0]
	v_cvt_pk_bf16_f32 v48, v52, v53
	v_pk_mul_f32 v[54:55], v[54:55], v[66:67] op_sel_hi:[1,0]
	s_and_b64 vcc, exec, s[6:7]
	v_cvt_pk_bf16_f32 v49, v54, v55
	v_cvt_pk_bf16_f32 v50, v50, v51
	v_cvt_pk_bf16_f32 v51, v56, v57
	global_store_dwordx4 v[68:69], v[48:51], off offset:256
	s_nop 1
	v_add_u32_e32 v48, 0x90, v160
	v_ashrrev_i32_e32 v49, 31, v48
	s_cbranch_vccnz .LBB0_1181
	v_mul_f32_e32 v64, 0x39010204, v204
.LBB0_1181:
	v_cvt_f32_i32_e32 v45, v45
	v_cvt_f32_i32_e32 v47, v47
	v_cvt_f32_i32_e32 v46, v46
	v_cvt_f32_i32_e32 v44, v44
	v_cvt_f32_i32_e32 v41, v41
	v_cvt_f32_i32_e32 v43, v43
	v_cvt_f32_i32_e32 v42, v42
	v_cvt_f32_i32_e32 v40, v40
	v_cvt_f32_i32_e32 v37, v37
	v_cvt_f32_i32_e32 v36, v36
	v_cvt_f32_i32_e32 v33, v33
	v_cvt_f32_i32_e32 v35, v35
	v_cvt_f32_i32_e32 v34, v34
	v_cvt_f32_i32_e32 v32, v32
	v_cvt_f32_i32_e32 v39, v39
	v_cvt_f32_i32_e32 v38, v38
	v_lshlrev_b64 v[48:49], 13, v[48:49]
	v_lshl_add_u64 v[48:49], s[36:37], 0, v[48:49]
	v_pk_mul_f32 v[46:47], v[122:123], v[46:47]
	v_pk_mul_f32 v[44:45], v[120:121], v[44:45]
	v_pk_mul_f32 v[42:43], v[114:115], v[42:43]
	v_pk_mul_f32 v[40:41], v[112:113], v[40:41]
	v_lshl_add_u64 v[48:49], v[158:159], 1, v[48:49]
	v_pk_mul_f32 v[46:47], v[46:47], v[64:65] op_sel_hi:[1,0]
	v_pk_mul_f32 v[44:45], v[44:45], v[64:65] op_sel_hi:[1,0]
	v_pk_mul_f32 v[50:51], v[42:43], v[64:65] op_sel_hi:[1,0]
	v_pk_mul_f32 v[42:43], v[40:41], v[64:65] op_sel_hi:[1,0]
	v_cvt_pk_bf16_f32 v40, v44, v45
	v_cvt_pk_bf16_f32 v41, v46, v47
	v_pk_mul_f32 v[36:37], v[108:109], v[36:37]
	v_pk_mul_f32 v[34:35], v[106:107], v[34:35]
	v_pk_mul_f32 v[32:33], v[104:105], v[32:33]
	v_cvt_pk_bf16_f32 v42, v42, v43
	v_cvt_pk_bf16_f32 v43, v50, v51
	global_store_dwordx4 v[48:49], v[40:43], off
	v_pk_mul_f32 v[38:39], v[110:111], v[38:39]
	v_pk_mul_f32 v[36:37], v[36:37], v[64:65] op_sel_hi:[1,0]
	v_pk_mul_f32 v[40:41], v[34:35], v[64:65] op_sel_hi:[1,0]
	v_pk_mul_f32 v[34:35], v[32:33], v[64:65] op_sel_hi:[1,0]
	v_pk_mul_f32 v[38:39], v[38:39], v[64:65] op_sel_hi:[1,0]
	v_cvt_pk_bf16_f32 v32, v36, v37
	v_add_u32_e32 v36, 0xa0, v160
	v_cvt_pk_bf16_f32 v33, v38, v39
	v_cvt_pk_bf16_f32 v34, v34, v35
	v_cvt_pk_bf16_f32 v35, v40, v41
	global_store_dwordx4 v[48:49], v[32:35], off offset:256
	v_ashrrev_i32_e32 v37, 31, v36
	s_and_b64 vcc, exec, s[6:7]
	v_mov_b32_e32 v32, 0x39010204
	v_mov_b32_e32 v34, 0x39010204
	s_cbranch_vccnz .LBB0_1183
	v_mul_f32_e32 v34, 0x39010204, v205
.LBB0_1183:
	v_cvt_f32_i32_e32 v29, v29
	v_cvt_f32_i32_e32 v31, v31
	v_cvt_f32_i32_e32 v30, v30
	v_cvt_f32_i32_e32 v28, v28
	v_cvt_f32_i32_e32 v25, v25
	v_cvt_f32_i32_e32 v27, v27
	v_cvt_f32_i32_e32 v26, v26
	v_cvt_f32_i32_e32 v24, v24
	v_cvt_f32_i32_e32 v21, v21
	v_cvt_f32_i32_e32 v20, v20
	v_cvt_f32_i32_e32 v17, v17
	v_cvt_f32_i32_e32 v19, v19
	v_cvt_f32_i32_e32 v18, v18
	v_cvt_f32_i32_e32 v16, v16
	v_cvt_f32_i32_e32 v23, v23
	v_cvt_f32_i32_e32 v22, v22
	v_lshlrev_b64 v[36:37], 13, v[36:37]
	v_lshl_add_u64 v[36:37], s[36:37], 0, v[36:37]
	v_pk_mul_f32 v[30:31], v[122:123], v[30:31]
	v_pk_mul_f32 v[28:29], v[120:121], v[28:29]
	v_pk_mul_f32 v[26:27], v[114:115], v[26:27]
	v_pk_mul_f32 v[24:25], v[112:113], v[24:25]
	v_lshl_add_u64 v[36:37], v[158:159], 1, v[36:37]
	v_pk_mul_f32 v[30:31], v[30:31], v[34:35] op_sel_hi:[1,0]
	v_pk_mul_f32 v[28:29], v[28:29], v[34:35] op_sel_hi:[1,0]
	v_pk_mul_f32 v[38:39], v[26:27], v[34:35] op_sel_hi:[1,0]
	v_pk_mul_f32 v[26:27], v[24:25], v[34:35] op_sel_hi:[1,0]
	v_cvt_pk_bf16_f32 v24, v28, v29
	v_cvt_pk_bf16_f32 v25, v30, v31
	v_pk_mul_f32 v[20:21], v[108:109], v[20:21]
	v_pk_mul_f32 v[18:19], v[106:107], v[18:19]
	v_pk_mul_f32 v[16:17], v[104:105], v[16:17]
	v_cvt_pk_bf16_f32 v26, v26, v27
	v_cvt_pk_bf16_f32 v27, v38, v39
	global_store_dwordx4 v[36:37], v[24:27], off
	v_pk_mul_f32 v[22:23], v[110:111], v[22:23]
	v_pk_mul_f32 v[20:21], v[20:21], v[34:35] op_sel_hi:[1,0]
	v_pk_mul_f32 v[24:25], v[18:19], v[34:35] op_sel_hi:[1,0]
	v_pk_mul_f32 v[18:19], v[16:17], v[34:35] op_sel_hi:[1,0]
	v_cvt_pk_bf16_f32 v16, v20, v21
	v_pk_mul_f32 v[22:23], v[22:23], v[34:35] op_sel_hi:[1,0]
	s_and_b64 vcc, exec, s[6:7]
	v_cvt_pk_bf16_f32 v17, v22, v23
	v_cvt_pk_bf16_f32 v18, v18, v19
	v_cvt_pk_bf16_f32 v19, v24, v25
	global_store_dwordx4 v[36:37], v[16:19], off offset:256
	s_nop 1
	v_add_u32_e32 v16, 0xb0, v160
	v_ashrrev_i32_e32 v17, 31, v16
	s_cbranch_vccnz .LBB0_1185
	v_mul_f32_e32 v32, 0x39010204, v206
